# FoX: next-tile forget-gate bound load hoisted to start of the fast path (was issued and waited right after PV)
# speedup vs baseline: 1.0425x; 1.0044x over previous
; template <int MODE, int DK, bool PASS2> ...
;     ...
;                     if (MODE == M_FOX) {
;                         if (has) { const float cn = cg2[jn * 64 + 63]; dead = __builtin_amdgcn_ballot_w64(!((qnb - cn) - m_run < -160.0f)) == 0ull; }
;                     }
.Lfox_cn_ready:
	v_sub_f32_e32 v2, v226, v2
	v_sub_f32_e32 v2, v2, v4
	v_cmp_ngt_f32_e32 vcc, s84, v2
	s_cmp_eq_u64 vcc, 0
	s_cselect_b64 s[52:53], -1, 0
	v_cndmask_b32_e64 v2, 0, 1, s[52:53]

; __device__ __forceinline__ float fexp2(float x) { return __builtin_amdgcn_exp2f(x); }
; __device__ __forceinline__ float fmax3(float a, float b, float c) { float d; asm("v_max3_f32 %0, %1, %2, %3" : "=v"(d) : "v"(a), "v"(b), "v"(c)); return d; }
; template <int MODE, int DK, bool PASS2> ...
;     ...
;                     float mx = fmaxf(s0[0], s1[0]);
; #pragma unroll
;                     for (int r = 1; r < 16; ++r) mx = fmax3(mx, s0[r], s1[r]);
;                     if (MODE == M_SLC) mx = selbit ? mx : NEG;
;                     mx = xhalf_max(mx);
;                     const float mxs = mx * sl2;
;                     const float mn = (mxs > m_run + 8.0f) ? mxs : m_run;
;                     const float alpha = fexp2(m_run - mn);
;                     m_run = mn;
;                     float nm = -mn;
;                     if (MODE == M_SLC) nm = selbit ? nm : -__builtin_inff();
;                     float ps0 = 0.f, ps1 = 0.f;
; #pragma unroll
;                     for (int r = 0; r < 16; ++r) {
;                         s0[r] = fexp2(__builtin_fmaf(s0[r], sl2, nm)); s1[r] = fexp2(__builtin_fmaf(s1[r], sl2, nm));
;                         ps0 += s0[r]; ps1 += s1[r];
;                     }
;                     l_run = l_run * alpha + (ps0 + ps1);
;                     if (__builtin_amdgcn_ballot_w64(alpha != 1.0f) != 0ull) {
; #pragma unroll
;                         for (int db = 0; db < 4; ++db)
; #pragma unroll
;                             for (int r = 0; r < 16; ++r) O[db][r] *= alpha;
;                     }
;     ...
;                     if (MODE == M_FOX) {
;                         if (has) { const float cn = cg2[jn * 64 + 63]; dead = __builtin_amdgcn_ballot_w64(!((qnb - cn) - m_run < -160.0f)) == 0ull; }
;                     }
.Lfast_fox:
	s_mul_i32 s98, s86, 0x4800
	v_add_u32_e32 v252, s98, v231
	ds_read_b128 v[240:243], v252 offset:34816
	ds_read_b128 v[244:247], v252 offset:39424
	ds_read_b128 v[248:251], v252 offset:44032
	s_and_b64 vcc, exec, s[10:11]
	s_cbranch_vccnz .Lfast_fox_noload
	s_add_i32 s24, s87, 0xffffff81
	s_lshl_b64 s[52:53], s[24:25], 2
	s_add_u32 s52, s36, s52
	s_addc_u32 s53, s37, s53
	global_load_dword v145, v3, s[52:53] offset:252
.Lfast_fox_noload:
	v_max_f32_e32 v124, v98, v99
	v_max_f32_e32 v125, v82, v83
	v_max3_f32 v124, v124, v100, v101
	v_max3_f32 v125, v125, v84, v85
	v_max3_f32 v124, v124, v102, v103
	v_max3_f32 v125, v125, v86, v87
	v_max3_f32 v124, v124, v104, v105
	v_max3_f32 v125, v125, v88, v89
	v_max3_f32 v124, v124, v106, v107
	v_max3_f32 v125, v125, v90, v91
	v_max3_f32 v124, v124, v108, v109
	v_max3_f32 v125, v125, v92, v93
	v_max3_f32 v124, v124, v110, v111
	v_max3_f32 v125, v125, v94, v95
	v_max3_f32 v124, v124, v112, v113
	v_max3_f32 v125, v125, v96, v97
	v_max_f32_e32 v124, v124, v125
	v_mov_b32_e32 v125, v124
	s_nop 1
	v_permlane32_swap_b32_e32 v124, v125
	v_max_f32_e32 v124, v124, v125
	v_mul_f32_e32 v124, 0x3e0293ee, v124
	v_cmp_gt_f32_e32 vcc, v124, v2
	s_nop 1
	v_cndmask_b32_e32 v4, v239, v124, vcc
	v_sub_f32_e32 v125, v239, v4
	v_exp_f32_e32 v2, v125
	s_nop 0
	v_cmp_neq_f32_e32 vcc, 1.0, v2
	s_cbranch_vccz .Lfast_fox_norescale
	v_pk_mul_f32 v[80:81], v[80:81], v[2:3] op_sel_hi:[1,0]
	v_pk_mul_f32 v[78:79], v[78:79], v[2:3] op_sel_hi:[1,0]
	v_pk_mul_f32 v[76:77], v[76:77], v[2:3] op_sel_hi:[1,0]
	v_pk_mul_f32 v[74:75], v[74:75], v[2:3] op_sel_hi:[1,0]
	v_pk_mul_f32 v[72:73], v[72:73], v[2:3] op_sel_hi:[1,0]
	v_pk_mul_f32 v[70:71], v[70:71], v[2:3] op_sel_hi:[1,0]
	v_pk_mul_f32 v[68:69], v[68:69], v[2:3] op_sel_hi:[1,0]
	v_pk_mul_f32 v[66:67], v[66:67], v[2:3] op_sel_hi:[1,0]
	v_pk_mul_f32 v[64:65], v[64:65], v[2:3] op_sel_hi:[1,0]
	v_pk_mul_f32 v[62:63], v[62:63], v[2:3] op_sel_hi:[1,0]
	v_pk_mul_f32 v[60:61], v[60:61], v[2:3] op_sel_hi:[1,0]
	v_pk_mul_f32 v[58:59], v[58:59], v[2:3] op_sel_hi:[1,0]
	v_pk_mul_f32 v[56:57], v[56:57], v[2:3] op_sel_hi:[1,0]
	v_pk_mul_f32 v[54:55], v[54:55], v[2:3] op_sel_hi:[1,0]
	v_pk_mul_f32 v[52:53], v[52:53], v[2:3] op_sel_hi:[1,0]
	v_pk_mul_f32 v[50:51], v[50:51], v[2:3] op_sel_hi:[1,0]
	v_pk_mul_f32 v[48:49], v[48:49], v[2:3] op_sel_hi:[1,0]
	v_pk_mul_f32 v[46:47], v[46:47], v[2:3] op_sel_hi:[1,0]
	v_pk_mul_f32 v[44:45], v[44:45], v[2:3] op_sel_hi:[1,0]
	v_pk_mul_f32 v[42:43], v[42:43], v[2:3] op_sel_hi:[1,0]
	v_pk_mul_f32 v[40:41], v[40:41], v[2:3] op_sel_hi:[1,0]
	v_pk_mul_f32 v[38:39], v[38:39], v[2:3] op_sel_hi:[1,0]
	v_pk_mul_f32 v[36:37], v[36:37], v[2:3] op_sel_hi:[1,0]
	v_pk_mul_f32 v[34:35], v[34:35], v[2:3] op_sel_hi:[1,0]
	v_pk_mul_f32 v[32:33], v[32:33], v[2:3] op_sel_hi:[1,0]
	v_pk_mul_f32 v[30:31], v[30:31], v[2:3] op_sel_hi:[1,0]
	v_pk_mul_f32 v[28:29], v[28:29], v[2:3] op_sel_hi:[1,0]
	v_pk_mul_f32 v[26:27], v[26:27], v[2:3] op_sel_hi:[1,0]
	v_pk_mul_f32 v[24:25], v[24:25], v[2:3] op_sel_hi:[1,0]
	v_pk_mul_f32 v[22:23], v[22:23], v[2:3] op_sel_hi:[1,0]
	v_pk_mul_f32 v[20:21], v[20:21], v[2:3] op_sel_hi:[1,0]
	v_pk_mul_f32 v[18:19], v[18:19], v[2:3] op_sel_hi:[1,0]
; #define LAS __attribute__((address_space(3)))
; __device__ __forceinline__ unsigned pack2(float lo, float hi) { unsigned r; asm volatile("v_cvt_pk_bf16_f32 %0, %1, %2" : "=v"(r) : "v"(lo), "v"(hi)); return r; }
; __device__ __forceinline__ float fexp2(float x) { return __builtin_amdgcn_exp2f(x); }
; __device__ __forceinline__ f32x16 mfma32(bf16x8 a, bf16x8 b, f32x16 c) { return __builtin_amdgcn_mfma_f32_32x32x16_bf16(a, b, c, 0, 0, 0); }
; template <int MODE, int DK, bool PASS2> ...
;     ...
;                     float ps0 = 0.f, ps1 = 0.f;
; #pragma unroll
;                     for (int r = 0; r < 16; ++r) {
;                         s0[r] = fexp2(__builtin_fmaf(s0[r], sl2, nm)); s1[r] = fexp2(__builtin_fmaf(s1[r], sl2, nm));
;                         ps0 += s0[r]; ps1 += s1[r];
;                     }
;                     l_run = l_run * alpha + (ps0 + ps1);
;     ...
;                 if (!PASS2) {
;                     bf16x8 pf[4];
; #pragma unroll
;                     for (int k2 = 0; k2 < 4; ++k2) {
;                         u32x4 pk;
; #pragma unroll
;                         for (int e = 0; e < 4; ++e) pk[e] = (k2 < 2) ? pack2(s0[(k2 & 1) * 8 + 2 * e], s0[(k2 & 1) * 8 + 2 * e + 1]) : pack2(s1[(k2 & 1) * 8 + 2 * e], s1[(k2 & 1) * 8 + 2 * e + 1]);
;                         pf[k2] = __builtin_bit_cast(bf16x8, pk);
;                     }
;                     const LAS unsigned char* vb = lds + F_VB0 + buf * F_VBS + ql * 144 + g * 16;
;                     __builtin_amdgcn_s_setprio(1);
; #pragma unroll
;                     for (int db = 0; db < 4; ++db)
; #pragma unroll
;                         for (int k2 = 0; k2 < 4; ++k2) {
;                             const bf16x8 vf = *(const LAS bf16x8*)(vb + db * 32 * 144 + k2 * 32);
;                             O[db] = mfma32(vf, pf[k2], O[db]);
;                             if (k2 == 3 && (db & 1)) __builtin_amdgcn_sched_barrier(0);
;                         }
;                     __builtin_amdgcn_s_setprio(0);
;                     if (MODE == M_FOX) {
;                         if (has) { const float cn = cg2[jn * 64 + 63]; dead = __builtin_amdgcn_ballot_w64(!((qnb - cn) - m_run < -160.0f)) == 0ull; }
;                     }
.Lfast_fox_norescale:
	v_fma_f32 v118, v98, s83, -v4
	v_fma_f32 v119, v99, s83, -v4
	v_exp_f32_e32 v6, v118
	v_exp_f32_e32 v7, v119
	v_fma_f32 v120, v100, s83, -v4
	v_fma_f32 v121, v101, s83, -v4
	v_exp_f32_e32 v8, v120
	v_exp_f32_e32 v9, v121
	v_add_f32_e32 v122, v6, v7
	v_fma_f32 v118, v102, s83, -v4
	v_fma_f32 v119, v103, s83, -v4
	v_exp_f32_e32 v114, v118
	v_exp_f32_e32 v115, v119
	v_cvt_pk_bf16_f32 v98, v6, v7
	v_add_f32_e32 v122, v122, v8
	v_fma_f32 v120, v104, s83, -v4
	v_add_f32_e32 v122, v122, v9
	v_fma_f32 v121, v105, s83, -v4
	v_exp_f32_e32 v116, v120
	v_exp_f32_e32 v117, v121
	v_cvt_pk_bf16_f32 v99, v8, v9
	v_add_f32_e32 v122, v122, v114
	v_add_f32_e32 v122, v122, v115
	v_cvt_pk_bf16_f32 v100, v114, v115
	v_add_f32_e32 v122, v122, v116
	v_add_f32_e32 v122, v122, v117
	v_cvt_pk_bf16_f32 v101, v116, v117
	s_setprio 1
	v_fma_f32 v118, v106, s83, -v4
	v_fma_f32 v119, v107, s83, -v4
	s_waitcnt lgkmcnt(2)
	v_mfma_f32_32x32x16_bf16 v[66:81], v[240:243], v[98:101], v[66:81]
	v_exp_f32_e32 v6, v118
	v_exp_f32_e32 v7, v119
	v_fma_f32 v120, v108, s83, -v4
	v_fma_f32 v121, v109, s83, -v4
	v_exp_f32_e32 v8, v120
	v_exp_f32_e32 v9, v121
	s_waitcnt lgkmcnt(1)
	v_mfma_f32_32x32x16_bf16 v[50:65], v[244:247], v[98:101], v[50:65]
	ds_read_b128 v[240:243], v252 offset:48640
	v_add_f32_e32 v122, v122, v6
	v_fma_f32 v118, v110, s83, -v4
	v_add_f32_e32 v122, v122, v7
	v_fma_f32 v119, v111, s83, -v4
	v_exp_f32_e32 v114, v118
	v_exp_f32_e32 v115, v119
	s_waitcnt lgkmcnt(1)
	v_mfma_f32_32x32x16_bf16 v[34:49], v[248:251], v[98:101], v[34:49]
	ds_read_b128 v[244:247], v252 offset:34848
	v_cvt_pk_bf16_f32 v106, v6, v7
	v_add_f32_e32 v122, v122, v8
	v_fma_f32 v120, v112, s83, -v4
	v_add_f32_e32 v122, v122, v9
	v_fma_f32 v121, v113, s83, -v4
	v_exp_f32_e32 v116, v120
	s_waitcnt lgkmcnt(1)
	v_mfma_f32_32x32x16_bf16 v[18:33], v[240:243], v[98:101], v[18:33]
	ds_read_b128 v[248:251], v252 offset:39456
	v_exp_f32_e32 v117, v121
	v_cvt_pk_bf16_f32 v107, v8, v9
	v_add_f32_e32 v122, v122, v114
	v_add_f32_e32 v122, v122, v115
	v_cvt_pk_bf16_f32 v108, v114, v115
	v_add_f32_e32 v122, v122, v116
	v_add_f32_e32 v122, v122, v117
	v_cvt_pk_bf16_f32 v109, v116, v117
	v_fma_f32 v118, v82, s83, -v4
	v_fma_f32 v119, v83, s83, -v4
	s_waitcnt lgkmcnt(1)
	v_mfma_f32_32x32x16_bf16 v[66:81], v[244:247], v[106:109], v[66:81]
	ds_read_b128 v[240:243], v252 offset:44064
	v_exp_f32_e32 v6, v118
	v_exp_f32_e32 v7, v119
	v_fma_f32 v120, v84, s83, -v4
	v_fma_f32 v121, v85, s83, -v4
	v_exp_f32_e32 v8, v120
	v_exp_f32_e32 v9, v121
	s_waitcnt lgkmcnt(1)
	v_mfma_f32_32x32x16_bf16 v[50:65], v[248:251], v[106:109], v[50:65]
	ds_read_b128 v[244:247], v252 offset:48672
	v_add_f32_e32 v123, v6, v7
	v_fma_f32 v118, v86, s83, -v4
	v_fma_f32 v119, v87, s83, -v4
	v_exp_f32_e32 v114, v118
	v_exp_f32_e32 v115, v119
	v_cvt_pk_bf16_f32 v82, v6, v7
	s_waitcnt lgkmcnt(1)
	v_mfma_f32_32x32x16_bf16 v[34:49], v[240:243], v[106:109], v[34:49]
	ds_read_b128 v[248:251], v252 offset:34880
	v_add_f32_e32 v123, v123, v8
	v_fma_f32 v120, v88, s83, -v4
	v_add_f32_e32 v123, v123, v9
	v_fma_f32 v121, v89, s83, -v4
	v_exp_f32_e32 v116, v120
	v_exp_f32_e32 v117, v121
	s_waitcnt lgkmcnt(1)
	v_mfma_f32_32x32x16_bf16 v[18:33], v[244:247], v[106:109], v[18:33]
	ds_read_b128 v[240:243], v252 offset:39488
	v_cvt_pk_bf16_f32 v83, v8, v9
	v_add_f32_e32 v123, v123, v114
	v_add_f32_e32 v123, v123, v115
	v_cvt_pk_bf16_f32 v84, v114, v115
	v_add_f32_e32 v123, v123, v116
	v_add_f32_e32 v123, v123, v117
	v_cvt_pk_bf16_f32 v85, v116, v117
	v_fma_f32 v118, v90, s83, -v4
	v_fma_f32 v119, v91, s83, -v4
	s_waitcnt lgkmcnt(1)
	v_mfma_f32_32x32x16_bf16 v[66:81], v[248:251], v[82:85], v[66:81]
	ds_read_b128 v[244:247], v252 offset:44096
	v_exp_f32_e32 v6, v118
	v_exp_f32_e32 v7, v119
	v_fma_f32 v120, v92, s83, -v4
	v_fma_f32 v121, v93, s83, -v4
	v_exp_f32_e32 v8, v120
	v_exp_f32_e32 v9, v121
	s_waitcnt lgkmcnt(1)
	v_mfma_f32_32x32x16_bf16 v[50:65], v[240:243], v[82:85], v[50:65]
	ds_read_b128 v[248:251], v252 offset:48704
	v_add_f32_e32 v123, v123, v6
	v_fma_f32 v118, v94, s83, -v4
	v_add_f32_e32 v123, v123, v7
	v_fma_f32 v119, v95, s83, -v4
	v_exp_f32_e32 v114, v118
	v_exp_f32_e32 v115, v119
	s_waitcnt lgkmcnt(1)
	v_mfma_f32_32x32x16_bf16 v[34:49], v[244:247], v[82:85], v[34:49]
	ds_read_b128 v[240:243], v252 offset:34912
	v_cvt_pk_bf16_f32 v90, v6, v7
	v_add_f32_e32 v123, v123, v8
	v_fma_f32 v120, v96, s83, -v4
	v_add_f32_e32 v123, v123, v9
	v_fma_f32 v121, v97, s83, -v4
	v_exp_f32_e32 v116, v120
	s_waitcnt lgkmcnt(1)
	v_mfma_f32_32x32x16_bf16 v[18:33], v[248:251], v[82:85], v[18:33]
	ds_read_b128 v[244:247], v252 offset:39520
	v_exp_f32_e32 v117, v121
	v_cvt_pk_bf16_f32 v91, v8, v9
	v_add_f32_e32 v123, v123, v114
	v_add_f32_e32 v123, v123, v115
	v_cvt_pk_bf16_f32 v92, v114, v115
	v_add_f32_e32 v123, v123, v116
	v_add_f32_e32 v123, v123, v117
	v_cvt_pk_bf16_f32 v93, v116, v117
	v_add_f32_e32 v5, v122, v123
	s_waitcnt lgkmcnt(1)
	v_mfma_f32_32x32x16_bf16 v[66:81], v[240:243], v[90:93], v[66:81]
	ds_read_b128 v[248:251], v252 offset:44128
	v_fmac_f32_e32 v5, v238, v2
	s_waitcnt lgkmcnt(1)
	v_mfma_f32_32x32x16_bf16 v[50:65], v[244:247], v[90:93], v[50:65]
	ds_read_b128 v[240:243], v252 offset:48736
	s_waitcnt lgkmcnt(1)
	v_mfma_f32_32x32x16_bf16 v[34:49], v[248:251], v[90:93], v[34:49]
	s_waitcnt lgkmcnt(0)
	v_mfma_f32_32x32x16_bf16 v[18:33], v[240:243], v[90:93], v[18:33]
	s_setprio 0
	s_and_b64 vcc, exec, s[10:11]
	s_cbranch_vccnz .Lpostpv_fox
	s_waitcnt vmcnt(0)
	v_mov_b32_e32 v2, v145
	s_branch .Lfox_cn_ready
	s_branch .Lpostpv_fox

; #define LAS __attribute__((address_space(3)))
; __device__ __forceinline__ unsigned pack2(float lo, float hi) { unsigned r; asm volatile("v_cvt_pk_bf16_f32 %0, %1, %2" : "=v"(r) : "v"(lo), "v"(hi)); return r; }
; __device__ __forceinline__ float fexp2(float x) { return __builtin_amdgcn_exp2f(x); }
; __device__ __forceinline__ f32x16 mfma32(bf16x8 a, bf16x8 b, f32x16 c) { return __builtin_amdgcn_mfma_f32_32x32x16_bf16(a, b, c, 0, 0, 0); }
; template <int MODE, int DK, bool PASS2> ...
;     ...
;                     float ps0 = 0.f, ps1 = 0.f;
; #pragma unroll
;                     for (int r = 0; r < 16; ++r) {
;                         s0[r] = fexp2(__builtin_fmaf(s0[r], sl2, nm)); s1[r] = fexp2(__builtin_fmaf(s1[r], sl2, nm));
;                         ps0 += s0[r]; ps1 += s1[r];
;                     }
;                     l_run = l_run * alpha + (ps0 + ps1);
;     ...
;                 if (!PASS2) {
;                     bf16x8 pf[4];
; #pragma unroll
;                     for (int k2 = 0; k2 < 4; ++k2) {
;                         u32x4 pk;
; #pragma unroll
;                         for (int e = 0; e < 4; ++e) pk[e] = (k2 < 2) ? pack2(s0[(k2 & 1) * 8 + 2 * e], s0[(k2 & 1) * 8 + 2 * e + 1]) : pack2(s1[(k2 & 1) * 8 + 2 * e], s1[(k2 & 1) * 8 + 2 * e + 1]);
;                         pf[k2] = __builtin_bit_cast(bf16x8, pk);
;                     }
;                     const LAS unsigned char* vb = lds + F_VB0 + buf * F_VBS + ql * 144 + g * 16;
;                     __builtin_amdgcn_s_setprio(1);
; #pragma unroll
;                     for (int db = 0; db < 4; ++db)
; #pragma unroll
;                         for (int k2 = 0; k2 < 4; ++k2) {
;                             const bf16x8 vf = *(const LAS bf16x8*)(vb + db * 32 * 144 + k2 * 32);
;                             O[db] = mfma32(vf, pf[k2], O[db]);
;                             if (k2 == 3 && (db & 1)) __builtin_amdgcn_sched_barrier(0);
;                         }
;                     __builtin_amdgcn_s_setprio(0);
.Lfast_diff_norescale:
	v_fma_f32 v12, v82, s12, -v207
	v_fma_f32 v13, v83, s12, -v207
	v_exp_f32_e32 v4, v12
	v_exp_f32_e32 v5, v13
	v_fma_f32 v14, v84, s12, -v207
	v_fma_f32 v15, v85, s12, -v207
	v_exp_f32_e32 v6, v14
	v_exp_f32_e32 v7, v15
	v_add_f32_e32 v16, v4, v5
	v_fma_f32 v12, v86, s12, -v207
	v_fma_f32 v13, v87, s12, -v207
	v_exp_f32_e32 v8, v12
	v_exp_f32_e32 v9, v13
	v_cvt_pk_bf16_f32 v236, v4, v5
	v_add_f32_e32 v16, v16, v6
	v_fma_f32 v14, v88, s12, -v207
	v_add_f32_e32 v16, v16, v7
	v_fma_f32 v15, v89, s12, -v207
	v_exp_f32_e32 v10, v14
	v_exp_f32_e32 v11, v15
	v_cvt_pk_bf16_f32 v237, v6, v7
	v_add_f32_e32 v16, v16, v8
	v_add_f32_e32 v16, v16, v9
	v_cvt_pk_bf16_f32 v238, v8, v9
	v_add_f32_e32 v16, v16, v10
	v_add_f32_e32 v16, v16, v11
	v_cvt_pk_bf16_f32 v239, v10, v11
	s_setprio 1
	v_fma_f32 v12, v90, s12, -v207
	v_fma_f32 v13, v91, s12, -v207
	s_waitcnt lgkmcnt(5)
	v_mfma_f32_32x32x16_bf16 v[66:81], v[212:215], v[236:239], v[66:81]
	v_exp_f32_e32 v4, v12
	v_exp_f32_e32 v5, v13
	v_fma_f32 v14, v92, s12, -v207
	v_fma_f32 v15, v93, s12, -v207
	v_exp_f32_e32 v6, v14
	v_exp_f32_e32 v7, v15
	s_waitcnt lgkmcnt(4)
	v_mfma_f32_32x32x16_bf16 v[50:65], v[216:219], v[236:239], v[50:65]
	ds_read_b128 v[212:215], v210 offset:44064
	v_add_f32_e32 v16, v16, v4
	v_fma_f32 v12, v94, s12, -v207
	v_add_f32_e32 v16, v16, v5
	v_fma_f32 v13, v95, s12, -v207
	v_exp_f32_e32 v8, v12
	v_exp_f32_e32 v9, v13
	s_waitcnt lgkmcnt(4)
	v_mfma_f32_32x32x16_bf16 v[34:49], v[220:223], v[236:239], v[34:49]
	ds_read_b128 v[216:219], v210 offset:48672
	v_cvt_pk_bf16_f32 v240, v4, v5
	v_add_f32_e32 v16, v16, v6
	v_fma_f32 v14, v96, s12, -v207
	v_add_f32_e32 v16, v16, v7
	v_fma_f32 v15, v97, s12, -v207
	v_exp_f32_e32 v10, v14
	s_waitcnt lgkmcnt(4)
	v_mfma_f32_32x32x16_bf16 v[18:33], v[224:227], v[236:239], v[18:33]
	ds_read_b128 v[220:223], v210 offset:34880
	v_exp_f32_e32 v11, v15
	v_cvt_pk_bf16_f32 v241, v6, v7
	v_add_f32_e32 v16, v16, v8
	v_add_f32_e32 v16, v16, v9
	v_cvt_pk_bf16_f32 v242, v8, v9
	v_add_f32_e32 v16, v16, v10
	v_add_f32_e32 v16, v16, v11
	v_cvt_pk_bf16_f32 v243, v10, v11
	v_fma_f32 v12, v98, s12, -v207
	v_fma_f32 v13, v99, s12, -v207
	s_waitcnt lgkmcnt(4)
	v_mfma_f32_32x32x16_bf16 v[66:81], v[228:231], v[240:243], v[66:81]
	ds_read_b128 v[224:227], v210 offset:39488
	v_exp_f32_e32 v4, v12
	v_exp_f32_e32 v5, v13
	v_fma_f32 v14, v100, s12, -v207
	v_fma_f32 v15, v101, s12, -v207
	v_exp_f32_e32 v6, v14
	v_exp_f32_e32 v7, v15
	s_waitcnt lgkmcnt(4)
	v_mfma_f32_32x32x16_bf16 v[50:65], v[232:235], v[240:243], v[50:65]
	ds_read_b128 v[228:231], v210 offset:44096
	v_add_f32_e32 v17, v4, v5
	v_fma_f32 v12, v102, s12, -v207
	v_fma_f32 v13, v103, s12, -v207
	v_exp_f32_e32 v8, v12
	v_exp_f32_e32 v9, v13
	v_cvt_pk_bf16_f32 v244, v4, v5
	s_waitcnt lgkmcnt(4)
	v_mfma_f32_32x32x16_bf16 v[34:49], v[212:215], v[240:243], v[34:49]
	ds_read_b128 v[232:235], v210 offset:48704
	v_add_f32_e32 v17, v17, v6
	v_fma_f32 v14, v104, s12, -v207
	v_add_f32_e32 v17, v17, v7
	v_fma_f32 v15, v105, s12, -v207
	v_exp_f32_e32 v10, v14
	v_exp_f32_e32 v11, v15
	s_waitcnt lgkmcnt(4)
	v_mfma_f32_32x32x16_bf16 v[18:33], v[216:219], v[240:243], v[18:33]
	ds_read_b128 v[212:215], v210 offset:34912
	v_cvt_pk_bf16_f32 v245, v6, v7
	v_add_f32_e32 v17, v17, v8
	v_add_f32_e32 v17, v17, v9
	v_cvt_pk_bf16_f32 v246, v8, v9
	v_add_f32_e32 v17, v17, v10
	v_add_f32_e32 v17, v17, v11
	v_cvt_pk_bf16_f32 v247, v10, v11
	v_fma_f32 v12, v106, s12, -v207
	v_fma_f32 v13, v107, s12, -v207
	s_waitcnt lgkmcnt(4)
	v_mfma_f32_32x32x16_bf16 v[66:81], v[220:223], v[244:247], v[66:81]
	ds_read_b128 v[216:219], v210 offset:39520
	v_exp_f32_e32 v4, v12
	v_exp_f32_e32 v5, v13
	v_fma_f32 v14, v108, s12, -v207
	v_fma_f32 v15, v109, s12, -v207
	v_exp_f32_e32 v6, v14
	v_exp_f32_e32 v7, v15
	s_waitcnt lgkmcnt(4)
	v_mfma_f32_32x32x16_bf16 v[50:65], v[224:227], v[244:247], v[50:65]
	ds_read_b128 v[220:223], v210 offset:44128
	v_add_f32_e32 v17, v17, v4
	v_fma_f32 v12, v110, s12, -v207
	v_add_f32_e32 v17, v17, v5
	v_fma_f32 v13, v111, s12, -v207
	v_exp_f32_e32 v8, v12
	v_exp_f32_e32 v9, v13
	s_waitcnt lgkmcnt(4)
	v_mfma_f32_32x32x16_bf16 v[34:49], v[228:231], v[244:247], v[34:49]
	ds_read_b128 v[224:227], v210 offset:48736
	v_cvt_pk_bf16_f32 v248, v4, v5
	v_add_f32_e32 v17, v17, v6
	v_fma_f32 v14, v112, s12, -v207
	v_add_f32_e32 v17, v17, v7
	v_fma_f32 v15, v113, s12, -v207
	v_exp_f32_e32 v10, v14
	s_waitcnt lgkmcnt(4)
	v_mfma_f32_32x32x16_bf16 v[18:33], v[232:235], v[244:247], v[18:33]
	v_exp_f32_e32 v11, v15
	v_cvt_pk_bf16_f32 v249, v6, v7
	v_add_f32_e32 v17, v17, v8
	v_add_f32_e32 v17, v17, v9
	v_cvt_pk_bf16_f32 v250, v8, v9
	v_add_f32_e32 v17, v17, v10
	v_add_f32_e32 v17, v17, v11
	v_cvt_pk_bf16_f32 v251, v10, v11
	v_add_f32_e32 v209, v16, v17
	s_waitcnt lgkmcnt(3)
	v_mfma_f32_32x32x16_bf16 v[66:81], v[212:215], v[248:251], v[66:81]
	v_fmac_f32_e32 v209, v206, v178
	s_waitcnt lgkmcnt(2)
	v_mfma_f32_32x32x16_bf16 v[50:65], v[216:219], v[248:251], v[50:65]
	s_waitcnt lgkmcnt(1)
	v_mfma_f32_32x32x16_bf16 v[34:49], v[220:223], v[248:251], v[34:49]
	s_waitcnt lgkmcnt(0)
	v_mfma_f32_32x32x16_bf16 v[18:33], v[224:227], v[248:251], v[18:33]
	s_setprio 0
	s_branch .Lpostpv_diff

; #define LAS __attribute__((address_space(3)))
; __device__ __forceinline__ unsigned pack2(float lo, float hi) { unsigned r; asm volatile("v_cvt_pk_bf16_f32 %0, %1, %2" : "=v"(r) : "v"(lo), "v"(hi)); return r; }
; __device__ __forceinline__ float fexp2(float x) { return __builtin_amdgcn_exp2f(x); }
; __device__ __forceinline__ f32x16 mfma32(bf16x8 a, bf16x8 b, f32x16 c) { return __builtin_amdgcn_mfma_f32_32x32x16_bf16(a, b, c, 0, 0, 0); }
; template <int MODE, int DK, bool PASS2> ...
;     ...
;                     float ps0 = 0.f, ps1 = 0.f;
; #pragma unroll
;                     for (int r = 0; r < 16; ++r) {
;                         s0[r] = fexp2(__builtin_fmaf(s0[r], sl2, nm)); s1[r] = fexp2(__builtin_fmaf(s1[r], sl2, nm));
;                         ps0 += s0[r]; ps1 += s1[r];
;                     }
;                     l_run = l_run * alpha + (ps0 + ps1);
;     ...
;                 if (!PASS2) {
;                     bf16x8 pf[4];
; #pragma unroll
;                     for (int k2 = 0; k2 < 4; ++k2) {
;                         u32x4 pk;
; #pragma unroll
;                         for (int e = 0; e < 4; ++e) pk[e] = (k2 < 2) ? pack2(s0[(k2 & 1) * 8 + 2 * e], s0[(k2 & 1) * 8 + 2 * e + 1]) : pack2(s1[(k2 & 1) * 8 + 2 * e], s1[(k2 & 1) * 8 + 2 * e + 1]);
;                         pf[k2] = __builtin_bit_cast(bf16x8, pk);
;                     }
;                     const LAS unsigned char* vb = lds + F_VB0 + buf * F_VBS + ql * 144 + g * 16;
;                     __builtin_amdgcn_s_setprio(1);
; #pragma unroll
;                     for (int db = 0; db < 4; ++db)
; #pragma unroll
;                         for (int k2 = 0; k2 < 4; ++k2) {
;                             const bf16x8 vf = *(const LAS bf16x8*)(vb + db * 32 * 144 + k2 * 32);
;                             O[db] = mfma32(vf, pf[k2], O[db]);
;                             if (k2 == 3 && (db & 1)) __builtin_amdgcn_sched_barrier(0);
;                         }
;                     __builtin_amdgcn_s_setprio(0);
.Lfast_win_norescale:
	v_fma_f32 v12, v98, s58, -v208
	v_fma_f32 v13, v99, s58, -v208
	v_exp_f32_e32 v4, v12
	v_exp_f32_e32 v5, v13
	v_fma_f32 v14, v100, s58, -v208
	v_fma_f32 v15, v101, s58, -v208
	v_exp_f32_e32 v6, v14
	v_exp_f32_e32 v7, v15
	v_add_f32_e32 v16, v4, v5
	v_fma_f32 v12, v102, s58, -v208
	v_fma_f32 v13, v103, s58, -v208
	v_exp_f32_e32 v8, v12
	v_exp_f32_e32 v9, v13
	v_cvt_pk_bf16_f32 v236, v4, v5
	v_add_f32_e32 v16, v16, v6
	v_fma_f32 v14, v104, s58, -v208
	v_add_f32_e32 v16, v16, v7
	v_fma_f32 v15, v105, s58, -v208
	v_exp_f32_e32 v10, v14
	v_exp_f32_e32 v11, v15
	v_cvt_pk_bf16_f32 v237, v6, v7
	v_add_f32_e32 v16, v16, v8
	v_add_f32_e32 v16, v16, v9
	v_cvt_pk_bf16_f32 v238, v8, v9
	v_add_f32_e32 v16, v16, v10
	v_add_f32_e32 v16, v16, v11
	v_cvt_pk_bf16_f32 v239, v10, v11
	s_setprio 1
	v_fma_f32 v12, v106, s58, -v208
	v_fma_f32 v13, v107, s58, -v208
	s_waitcnt lgkmcnt(5)
	v_mfma_f32_32x32x16_bf16 v[66:81], v[212:215], v[236:239], v[66:81]
	v_exp_f32_e32 v4, v12
	v_exp_f32_e32 v5, v13
	v_fma_f32 v14, v108, s58, -v208
	v_fma_f32 v15, v109, s58, -v208
	v_exp_f32_e32 v6, v14
	v_exp_f32_e32 v7, v15
	s_waitcnt lgkmcnt(4)
	v_mfma_f32_32x32x16_bf16 v[50:65], v[216:219], v[236:239], v[50:65]
	ds_read_b128 v[212:215], v210 offset:44064
	v_add_f32_e32 v16, v16, v4
	v_fma_f32 v12, v110, s58, -v208
	v_add_f32_e32 v16, v16, v5
	v_fma_f32 v13, v111, s58, -v208
	v_exp_f32_e32 v8, v12
	v_exp_f32_e32 v9, v13
	s_waitcnt lgkmcnt(4)
	v_mfma_f32_32x32x16_bf16 v[34:49], v[220:223], v[236:239], v[34:49]
	ds_read_b128 v[216:219], v210 offset:48672
	v_cvt_pk_bf16_f32 v240, v4, v5
	v_add_f32_e32 v16, v16, v6
	v_fma_f32 v14, v112, s58, -v208
	v_add_f32_e32 v16, v16, v7
	v_fma_f32 v15, v113, s58, -v208
	v_exp_f32_e32 v10, v14
	s_waitcnt lgkmcnt(4)
	v_mfma_f32_32x32x16_bf16 v[18:33], v[224:227], v[236:239], v[18:33]
	ds_read_b128 v[220:223], v210 offset:34880
	v_exp_f32_e32 v11, v15
	v_cvt_pk_bf16_f32 v241, v6, v7
	v_add_f32_e32 v16, v16, v8
	v_add_f32_e32 v16, v16, v9
	v_cvt_pk_bf16_f32 v242, v8, v9
	v_add_f32_e32 v16, v16, v10
	v_add_f32_e32 v16, v16, v11
	v_cvt_pk_bf16_f32 v243, v10, v11
	v_fma_f32 v12, v82, s58, -v208
	v_fma_f32 v13, v83, s58, -v208
	s_waitcnt lgkmcnt(4)
	v_mfma_f32_32x32x16_bf16 v[66:81], v[228:231], v[240:243], v[66:81]
	ds_read_b128 v[224:227], v210 offset:39488
	v_exp_f32_e32 v4, v12
	v_exp_f32_e32 v5, v13
	v_fma_f32 v14, v84, s58, -v208
	v_fma_f32 v15, v85, s58, -v208
	v_exp_f32_e32 v6, v14
	v_exp_f32_e32 v7, v15
	s_waitcnt lgkmcnt(4)
	v_mfma_f32_32x32x16_bf16 v[50:65], v[232:235], v[240:243], v[50:65]
	ds_read_b128 v[228:231], v210 offset:44096
	v_add_f32_e32 v17, v4, v5
	v_fma_f32 v12, v86, s58, -v208
	v_fma_f32 v13, v87, s58, -v208
	v_exp_f32_e32 v8, v12
	v_exp_f32_e32 v9, v13
	v_cvt_pk_bf16_f32 v244, v4, v5
	s_waitcnt lgkmcnt(4)
	v_mfma_f32_32x32x16_bf16 v[34:49], v[212:215], v[240:243], v[34:49]
	ds_read_b128 v[232:235], v210 offset:48704
	v_add_f32_e32 v17, v17, v6
	v_fma_f32 v14, v88, s58, -v208
	v_add_f32_e32 v17, v17, v7
	v_fma_f32 v15, v89, s58, -v208
	v_exp_f32_e32 v10, v14
	v_exp_f32_e32 v11, v15
	s_waitcnt lgkmcnt(4)
	v_mfma_f32_32x32x16_bf16 v[18:33], v[216:219], v[240:243], v[18:33]
	ds_read_b128 v[212:215], v210 offset:34912
	v_cvt_pk_bf16_f32 v245, v6, v7
	v_add_f32_e32 v17, v17, v8
	v_add_f32_e32 v17, v17, v9
	v_cvt_pk_bf16_f32 v246, v8, v9
	v_add_f32_e32 v17, v17, v10
	v_add_f32_e32 v17, v17, v11
	v_cvt_pk_bf16_f32 v247, v10, v11
	v_fma_f32 v12, v90, s58, -v208
	v_fma_f32 v13, v91, s58, -v208
	s_waitcnt lgkmcnt(4)
	v_mfma_f32_32x32x16_bf16 v[66:81], v[220:223], v[244:247], v[66:81]
	ds_read_b128 v[216:219], v210 offset:39520
	v_exp_f32_e32 v4, v12
	v_exp_f32_e32 v5, v13
	v_fma_f32 v14, v92, s58, -v208
	v_fma_f32 v15, v93, s58, -v208
	v_exp_f32_e32 v6, v14
	v_exp_f32_e32 v7, v15
	s_waitcnt lgkmcnt(4)
	v_mfma_f32_32x32x16_bf16 v[50:65], v[224:227], v[244:247], v[50:65]
	ds_read_b128 v[220:223], v210 offset:44128
	v_add_f32_e32 v17, v17, v4
	v_fma_f32 v12, v94, s58, -v208
	v_add_f32_e32 v17, v17, v5
	v_fma_f32 v13, v95, s58, -v208
	v_exp_f32_e32 v8, v12
	v_exp_f32_e32 v9, v13
	s_waitcnt lgkmcnt(4)
	v_mfma_f32_32x32x16_bf16 v[34:49], v[228:231], v[244:247], v[34:49]
	ds_read_b128 v[224:227], v210 offset:48736
	v_cvt_pk_bf16_f32 v248, v4, v5
	v_add_f32_e32 v17, v17, v6
	v_fma_f32 v14, v96, s58, -v208
	v_add_f32_e32 v17, v17, v7
	v_fma_f32 v15, v97, s58, -v208
	v_exp_f32_e32 v10, v14
	s_waitcnt lgkmcnt(4)
	v_mfma_f32_32x32x16_bf16 v[18:33], v[232:235], v[244:247], v[18:33]
	v_exp_f32_e32 v11, v15
	v_cvt_pk_bf16_f32 v249, v6, v7
	v_add_f32_e32 v17, v17, v8
	v_add_f32_e32 v17, v17, v9
	v_cvt_pk_bf16_f32 v250, v8, v9
	v_add_f32_e32 v17, v17, v10
	v_add_f32_e32 v17, v17, v11
	v_cvt_pk_bf16_f32 v251, v10, v11
	v_add_f32_e32 v209, v16, v17
	s_waitcnt lgkmcnt(3)
	v_mfma_f32_32x32x16_bf16 v[66:81], v[212:215], v[248:251], v[66:81]
	v_fmac_f32_e32 v209, v206, v2
	s_waitcnt lgkmcnt(2)
	v_mfma_f32_32x32x16_bf16 v[50:65], v[216:219], v[248:251], v[50:65]
	s_waitcnt lgkmcnt(1)
	v_mfma_f32_32x32x16_bf16 v[34:49], v[220:223], v[248:251], v[34:49]
	s_waitcnt lgkmcnt(0)
	v_mfma_f32_32x32x16_bf16 v[18:33], v[224:227], v[248:251], v[18:33]
	s_setprio 0
	s_branch .Lpostpv_win

; #define LAS __attribute__((address_space(3)))
; __device__ __forceinline__ unsigned pack2(float lo, float hi) { unsigned r; asm volatile("v_cvt_pk_bf16_f32 %0, %1, %2" : "=v"(r) : "v"(lo), "v"(hi)); return r; }
; __device__ __forceinline__ float fexp2(float x) { return __builtin_amdgcn_exp2f(x); }
; __device__ __forceinline__ f32x16 mfma32(bf16x8 a, bf16x8 b, f32x16 c) { return __builtin_amdgcn_mfma_f32_32x32x16_bf16(a, b, c, 0, 0, 0); }
; template <int MODE, int DK, bool PASS2> ...
;     ...
;                     float ps0 = 0.f, ps1 = 0.f;
; #pragma unroll
;                     for (int r = 0; r < 16; ++r) {
;                         s0[r] = fexp2(__builtin_fmaf(s0[r], sl2, nm)); s1[r] = fexp2(__builtin_fmaf(s1[r], sl2, nm));
;                         ps0 += s0[r]; ps1 += s1[r];
;                     }
;                     l_run = l_run * alpha + (ps0 + ps1);
;     ...
;                 if (!PASS2) {
;                     bf16x8 pf[4];
; #pragma unroll
;                     for (int k2 = 0; k2 < 4; ++k2) {
;                         u32x4 pk;
; #pragma unroll
;                         for (int e = 0; e < 4; ++e) pk[e] = (k2 < 2) ? pack2(s0[(k2 & 1) * 8 + 2 * e], s0[(k2 & 1) * 8 + 2 * e + 1]) : pack2(s1[(k2 & 1) * 8 + 2 * e], s1[(k2 & 1) * 8 + 2 * e + 1]);
;                         pf[k2] = __builtin_bit_cast(bf16x8, pk);
;                     }
;                     const LAS unsigned char* vb = lds + F_VB0 + buf * F_VBS + ql * 144 + g * 16;
;                     __builtin_amdgcn_s_setprio(1);
; #pragma unroll
;                     for (int db = 0; db < 4; ++db)
; #pragma unroll
;                         for (int k2 = 0; k2 < 4; ++k2) {
;                             const bf16x8 vf = *(const LAS bf16x8*)(vb + db * 32 * 144 + k2 * 32);
;                             O[db] = mfma32(vf, pf[k2], O[db]);
;                             if (k2 == 3 && (db & 1)) __builtin_amdgcn_sched_barrier(0);
;                         }
;                     __builtin_amdgcn_s_setprio(0);
.Lfast_cmp1_norescale:
	v_fma_f32 v12, v82, s34, -v250
	v_fma_f32 v13, v83, s34, -v250
	v_exp_f32_e32 v4, v12
	v_exp_f32_e32 v5, v13
	v_fma_f32 v14, v84, s34, -v250
	v_fma_f32 v15, v85, s34, -v250
	v_exp_f32_e32 v6, v14
	v_exp_f32_e32 v7, v15
	v_add_f32_e32 v16, v4, v5
	v_fma_f32 v12, v86, s34, -v250
	v_fma_f32 v13, v87, s34, -v250
	v_exp_f32_e32 v8, v12
	v_exp_f32_e32 v9, v13
	v_cvt_pk_bf16_f32 v82, v4, v5
	v_add_f32_e32 v16, v16, v6
	v_fma_f32 v14, v88, s34, -v250
	v_add_f32_e32 v16, v16, v7
	v_fma_f32 v15, v89, s34, -v250
	v_exp_f32_e32 v10, v14
	v_exp_f32_e32 v11, v15
	v_cvt_pk_bf16_f32 v83, v6, v7
	v_add_f32_e32 v16, v16, v8
	v_add_f32_e32 v16, v16, v9
	v_cvt_pk_bf16_f32 v84, v8, v9
	v_add_f32_e32 v16, v16, v10
	v_add_f32_e32 v16, v16, v11
	v_cvt_pk_bf16_f32 v85, v10, v11
	s_setprio 1
	v_fma_f32 v12, v90, s34, -v250
	v_fma_f32 v13, v91, s34, -v250
	s_waitcnt lgkmcnt(2)
	v_mfma_f32_32x32x16_bf16 v[66:81], v[204:207], v[82:85], v[66:81]
	v_exp_f32_e32 v4, v12
	v_exp_f32_e32 v5, v13
	v_fma_f32 v14, v92, s34, -v250
	v_fma_f32 v15, v93, s34, -v250
	v_exp_f32_e32 v6, v14
	v_exp_f32_e32 v7, v15
	s_waitcnt lgkmcnt(1)
	v_mfma_f32_32x32x16_bf16 v[50:65], v[208:211], v[82:85], v[50:65]
	ds_read_b128 v[204:207], v216 offset:48640
	v_add_f32_e32 v16, v16, v4
	v_fma_f32 v12, v94, s34, -v250
	v_add_f32_e32 v16, v16, v5
	v_fma_f32 v13, v95, s34, -v250
	v_exp_f32_e32 v8, v12
	v_exp_f32_e32 v9, v13
	s_waitcnt lgkmcnt(1)
	v_mfma_f32_32x32x16_bf16 v[34:49], v[212:215], v[82:85], v[34:49]
	ds_read_b128 v[208:211], v216 offset:34848
	v_cvt_pk_bf16_f32 v90, v4, v5
	v_add_f32_e32 v16, v16, v6
	v_fma_f32 v14, v96, s34, -v250
	v_add_f32_e32 v16, v16, v7
	v_fma_f32 v15, v97, s34, -v250
	v_exp_f32_e32 v10, v14
	s_waitcnt lgkmcnt(1)
	v_mfma_f32_32x32x16_bf16 v[18:33], v[204:207], v[82:85], v[18:33]
	ds_read_b128 v[212:215], v216 offset:39456
	v_exp_f32_e32 v11, v15
	v_cvt_pk_bf16_f32 v91, v6, v7
	v_add_f32_e32 v16, v16, v8
	v_add_f32_e32 v16, v16, v9
	v_cvt_pk_bf16_f32 v92, v8, v9
	v_add_f32_e32 v16, v16, v10
	v_add_f32_e32 v16, v16, v11
	v_cvt_pk_bf16_f32 v93, v10, v11
	v_fma_f32 v12, v98, s34, -v250
	v_fma_f32 v13, v99, s34, -v250
	s_waitcnt lgkmcnt(1)
	v_mfma_f32_32x32x16_bf16 v[66:81], v[208:211], v[90:93], v[66:81]
	ds_read_b128 v[204:207], v216 offset:44064
	v_exp_f32_e32 v4, v12
	v_exp_f32_e32 v5, v13
	v_fma_f32 v14, v100, s34, -v250
	v_fma_f32 v15, v101, s34, -v250
	v_exp_f32_e32 v6, v14
	v_exp_f32_e32 v7, v15
	s_waitcnt lgkmcnt(1)
	v_mfma_f32_32x32x16_bf16 v[50:65], v[212:215], v[90:93], v[50:65]
	ds_read_b128 v[208:211], v216 offset:48672
	v_add_f32_e32 v17, v4, v5
	v_fma_f32 v12, v102, s34, -v250
	v_fma_f32 v13, v103, s34, -v250
	v_exp_f32_e32 v8, v12
	v_exp_f32_e32 v9, v13
	v_cvt_pk_bf16_f32 v98, v4, v5
	s_waitcnt lgkmcnt(1)
	v_mfma_f32_32x32x16_bf16 v[34:49], v[204:207], v[90:93], v[34:49]
	ds_read_b128 v[212:215], v216 offset:34880
	v_add_f32_e32 v17, v17, v6
	v_fma_f32 v14, v104, s34, -v250
	v_add_f32_e32 v17, v17, v7
	v_fma_f32 v15, v105, s34, -v250
	v_exp_f32_e32 v10, v14
	v_exp_f32_e32 v11, v15
	s_waitcnt lgkmcnt(1)
	v_mfma_f32_32x32x16_bf16 v[18:33], v[208:211], v[90:93], v[18:33]
	ds_read_b128 v[204:207], v216 offset:39488
	v_cvt_pk_bf16_f32 v99, v6, v7
	v_add_f32_e32 v17, v17, v8
	v_add_f32_e32 v17, v17, v9
	v_cvt_pk_bf16_f32 v100, v8, v9
	v_add_f32_e32 v17, v17, v10
	v_add_f32_e32 v17, v17, v11
	v_cvt_pk_bf16_f32 v101, v10, v11
	v_fma_f32 v12, v106, s34, -v250
	v_fma_f32 v13, v107, s34, -v250
	s_waitcnt lgkmcnt(1)
	v_mfma_f32_32x32x16_bf16 v[66:81], v[212:215], v[98:101], v[66:81]
	ds_read_b128 v[208:211], v216 offset:44096
	v_exp_f32_e32 v4, v12
	v_exp_f32_e32 v5, v13
	v_fma_f32 v14, v108, s34, -v250
	v_fma_f32 v15, v109, s34, -v250
	v_exp_f32_e32 v6, v14
	v_exp_f32_e32 v7, v15
	s_waitcnt lgkmcnt(1)
	v_mfma_f32_32x32x16_bf16 v[50:65], v[204:207], v[98:101], v[50:65]
	ds_read_b128 v[212:215], v216 offset:48704
	v_add_f32_e32 v17, v17, v4
	v_fma_f32 v12, v110, s34, -v250
	v_add_f32_e32 v17, v17, v5
	v_fma_f32 v13, v111, s34, -v250
	v_exp_f32_e32 v8, v12
	v_exp_f32_e32 v9, v13
	s_waitcnt lgkmcnt(1)
	v_mfma_f32_32x32x16_bf16 v[34:49], v[208:211], v[98:101], v[34:49]
	ds_read_b128 v[204:207], v216 offset:34912
	v_cvt_pk_bf16_f32 v106, v4, v5
	v_add_f32_e32 v17, v17, v6
	v_fma_f32 v14, v112, s34, -v250
	v_add_f32_e32 v17, v17, v7
	v_fma_f32 v15, v113, s34, -v250
	v_exp_f32_e32 v10, v14
	s_waitcnt lgkmcnt(1)
	v_mfma_f32_32x32x16_bf16 v[18:33], v[212:215], v[98:101], v[18:33]
	ds_read_b128 v[208:211], v216 offset:39520
	v_exp_f32_e32 v11, v15
	v_cvt_pk_bf16_f32 v107, v6, v7
	v_add_f32_e32 v17, v17, v8
	v_add_f32_e32 v17, v17, v9
	v_cvt_pk_bf16_f32 v108, v8, v9
	v_add_f32_e32 v17, v17, v10
	v_add_f32_e32 v17, v17, v11
	v_cvt_pk_bf16_f32 v109, v10, v11
	v_add_f32_e32 v251, v16, v17
	s_waitcnt lgkmcnt(1)
	v_mfma_f32_32x32x16_bf16 v[66:81], v[204:207], v[106:109], v[66:81]
	ds_read_b128 v[212:215], v216 offset:44128
	v_fmac_f32_e32 v251, v248, v2
	s_waitcnt lgkmcnt(1)
	v_mfma_f32_32x32x16_bf16 v[50:65], v[208:211], v[106:109], v[50:65]
	ds_read_b128 v[204:207], v216 offset:48736
	s_waitcnt lgkmcnt(1)
	v_mfma_f32_32x32x16_bf16 v[34:49], v[212:215], v[106:109], v[34:49]
	s_waitcnt lgkmcnt(0)
	v_mfma_f32_32x32x16_bf16 v[18:33], v[204:207], v[106:109], v[18:33]
	s_setprio 0
	s_branch .Lpostpv_cmp1

; #define LAS __attribute__((address_space(3)))
; __device__ __forceinline__ unsigned pack2(float lo, float hi) { unsigned r; asm volatile("v_cvt_pk_bf16_f32 %0, %1, %2" : "=v"(r) : "v"(lo), "v"(hi)); return r; }
; __device__ __forceinline__ float fexp2(float x) { return __builtin_amdgcn_exp2f(x); }
; __device__ __forceinline__ f32x16 mfma32(bf16x8 a, bf16x8 b, f32x16 c) { return __builtin_amdgcn_mfma_f32_32x32x16_bf16(a, b, c, 0, 0, 0); }
; template <int MODE, int DK, bool PASS2> ...
;     ...
;                     if (MODE == M_SLC) nm = selbit ? nm : -__builtin_inff();
;                     float ps0 = 0.f, ps1 = 0.f;
; #pragma unroll
;                     for (int r = 0; r < 16; ++r) {
;                         s0[r] = fexp2(__builtin_fmaf(s0[r], sl2, nm)); s1[r] = fexp2(__builtin_fmaf(s1[r], sl2, nm));
;                         ps0 += s0[r]; ps1 += s1[r];
;                     }
;                     l_run = l_run * alpha + (ps0 + ps1);
;     ...
;                 if (!PASS2) {
;                     bf16x8 pf[4];
; #pragma unroll
;                     for (int k2 = 0; k2 < 4; ++k2) {
;                         u32x4 pk;
; #pragma unroll
;                         for (int e = 0; e < 4; ++e) pk[e] = (k2 < 2) ? pack2(s0[(k2 & 1) * 8 + 2 * e], s0[(k2 & 1) * 8 + 2 * e + 1]) : pack2(s1[(k2 & 1) * 8 + 2 * e], s1[(k2 & 1) * 8 + 2 * e + 1]);
;                         pf[k2] = __builtin_bit_cast(bf16x8, pk);
;                     }
;                     const LAS unsigned char* vb = lds + F_VB0 + buf * F_VBS + ql * 144 + g * 16;
;                     __builtin_amdgcn_s_setprio(1);
; #pragma unroll
;                     for (int db = 0; db < 4; ++db)
; #pragma unroll
;                         for (int k2 = 0; k2 < 4; ++k2) {
;                             const bf16x8 vf = *(const LAS bf16x8*)(vb + db * 32 * 144 + k2 * 32);
;                             O[db] = mfma32(vf, pf[k2], O[db]);
;                             if (k2 == 3 && (db & 1)) __builtin_amdgcn_sched_barrier(0);
;                         }
;                     __builtin_amdgcn_s_setprio(0);
.Lfast_slc_norescale:
	v_cndmask_b32_e64 v191, v195, -v218, s[4:5]
	v_fmamk_f32 v12, v98, 0x3e0293ee, v191
	v_fmamk_f32 v13, v99, 0x3e0293ee, v191
	v_exp_f32_e32 v4, v12
	v_exp_f32_e32 v5, v13
	v_fmamk_f32 v14, v100, 0x3e0293ee, v191
	v_fmamk_f32 v15, v101, 0x3e0293ee, v191
	v_exp_f32_e32 v6, v14
	v_exp_f32_e32 v7, v15
	v_add_f32_e32 v16, v4, v5
	v_fmamk_f32 v12, v102, 0x3e0293ee, v191
	v_fmamk_f32 v13, v103, 0x3e0293ee, v191
	v_exp_f32_e32 v8, v12
	v_exp_f32_e32 v9, v13
	v_cvt_pk_bf16_f32 v98, v4, v5
	v_add_f32_e32 v16, v16, v6
	v_fmamk_f32 v14, v104, 0x3e0293ee, v191
	v_add_f32_e32 v16, v16, v7
	v_fmamk_f32 v15, v105, 0x3e0293ee, v191
	v_exp_f32_e32 v10, v14
	v_exp_f32_e32 v11, v15
	v_cvt_pk_bf16_f32 v99, v6, v7
	v_add_f32_e32 v16, v16, v8
	v_add_f32_e32 v16, v16, v9
	v_cvt_pk_bf16_f32 v100, v8, v9
	v_add_f32_e32 v16, v16, v10
	v_add_f32_e32 v16, v16, v11
	v_cvt_pk_bf16_f32 v101, v10, v11
	s_setprio 1
	v_fmamk_f32 v12, v106, 0x3e0293ee, v191
	v_fmamk_f32 v13, v107, 0x3e0293ee, v191
	s_waitcnt lgkmcnt(5)
	v_mfma_f32_32x32x16_bf16 v[66:81], v[222:225], v[98:101], v[66:81]
	v_exp_f32_e32 v4, v12
	v_exp_f32_e32 v5, v13
	v_fmamk_f32 v14, v108, 0x3e0293ee, v191
	v_fmamk_f32 v15, v109, 0x3e0293ee, v191
	v_exp_f32_e32 v6, v14
	v_exp_f32_e32 v7, v15
	s_waitcnt lgkmcnt(4)
	v_mfma_f32_32x32x16_bf16 v[50:65], v[226:229], v[98:101], v[50:65]
	ds_read_b128 v[222:225], v220 offset:44064
	v_add_f32_e32 v16, v16, v4
	v_fmamk_f32 v12, v110, 0x3e0293ee, v191
	v_add_f32_e32 v16, v16, v5
	v_fmamk_f32 v13, v111, 0x3e0293ee, v191
	v_exp_f32_e32 v8, v12
	v_exp_f32_e32 v9, v13
	s_waitcnt lgkmcnt(4)
	v_mfma_f32_32x32x16_bf16 v[34:49], v[230:233], v[98:101], v[34:49]
	ds_read_b128 v[226:229], v220 offset:48672
	v_cvt_pk_bf16_f32 v106, v4, v5
	v_add_f32_e32 v16, v16, v6
	v_fmamk_f32 v14, v112, 0x3e0293ee, v191
	v_add_f32_e32 v16, v16, v7
	v_fmamk_f32 v15, v113, 0x3e0293ee, v191
	v_exp_f32_e32 v10, v14
	s_waitcnt lgkmcnt(4)
	v_mfma_f32_32x32x16_bf16 v[18:33], v[234:237], v[98:101], v[18:33]
	ds_read_b128 v[230:233], v220 offset:34880
	v_exp_f32_e32 v11, v15
	v_cvt_pk_bf16_f32 v107, v6, v7
	v_add_f32_e32 v16, v16, v8
	v_add_f32_e32 v16, v16, v9
	v_cvt_pk_bf16_f32 v108, v8, v9
	v_add_f32_e32 v16, v16, v10
	v_add_f32_e32 v16, v16, v11
	v_cvt_pk_bf16_f32 v109, v10, v11
	v_fmamk_f32 v12, v82, 0x3e0293ee, v191
	v_fmamk_f32 v13, v83, 0x3e0293ee, v191
	s_waitcnt lgkmcnt(4)
	v_mfma_f32_32x32x16_bf16 v[66:81], v[238:241], v[106:109], v[66:81]
	ds_read_b128 v[234:237], v220 offset:39488
	v_exp_f32_e32 v4, v12
	v_exp_f32_e32 v5, v13
	v_fmamk_f32 v14, v84, 0x3e0293ee, v191
	v_fmamk_f32 v15, v85, 0x3e0293ee, v191
	v_exp_f32_e32 v6, v14
	v_exp_f32_e32 v7, v15
	s_waitcnt lgkmcnt(4)
	v_mfma_f32_32x32x16_bf16 v[50:65], v[242:245], v[106:109], v[50:65]
	ds_read_b128 v[238:241], v220 offset:44096
	v_add_f32_e32 v17, v4, v5
	v_fmamk_f32 v12, v86, 0x3e0293ee, v191
	v_fmamk_f32 v13, v87, 0x3e0293ee, v191
	v_exp_f32_e32 v8, v12
	v_exp_f32_e32 v9, v13
	v_cvt_pk_bf16_f32 v82, v4, v5
	s_waitcnt lgkmcnt(4)
	v_mfma_f32_32x32x16_bf16 v[34:49], v[222:225], v[106:109], v[34:49]
	ds_read_b128 v[242:245], v220 offset:48704
	v_add_f32_e32 v17, v17, v6
	v_fmamk_f32 v14, v88, 0x3e0293ee, v191
	v_add_f32_e32 v17, v17, v7
	v_fmamk_f32 v15, v89, 0x3e0293ee, v191
	v_exp_f32_e32 v10, v14
	v_exp_f32_e32 v11, v15
	s_waitcnt lgkmcnt(4)
	v_mfma_f32_32x32x16_bf16 v[18:33], v[226:229], v[106:109], v[18:33]
	ds_read_b128 v[222:225], v220 offset:34912
	v_cvt_pk_bf16_f32 v83, v6, v7
	v_add_f32_e32 v17, v17, v8
	v_add_f32_e32 v17, v17, v9
	v_cvt_pk_bf16_f32 v84, v8, v9
	v_add_f32_e32 v17, v17, v10
	v_add_f32_e32 v17, v17, v11
	v_cvt_pk_bf16_f32 v85, v10, v11
	v_fmamk_f32 v12, v90, 0x3e0293ee, v191
	v_fmamk_f32 v13, v91, 0x3e0293ee, v191
	s_waitcnt lgkmcnt(4)
	v_mfma_f32_32x32x16_bf16 v[66:81], v[230:233], v[82:85], v[66:81]
	ds_read_b128 v[226:229], v220 offset:39520
	v_exp_f32_e32 v4, v12
	v_exp_f32_e32 v5, v13
	v_fmamk_f32 v14, v92, 0x3e0293ee, v191
	v_fmamk_f32 v15, v93, 0x3e0293ee, v191
	v_exp_f32_e32 v6, v14
	v_exp_f32_e32 v7, v15
	s_waitcnt lgkmcnt(4)
	v_mfma_f32_32x32x16_bf16 v[50:65], v[234:237], v[82:85], v[50:65]
	ds_read_b128 v[230:233], v220 offset:44128
	v_add_f32_e32 v17, v17, v4
	v_fmamk_f32 v12, v94, 0x3e0293ee, v191
	v_add_f32_e32 v17, v17, v5
	v_fmamk_f32 v13, v95, 0x3e0293ee, v191
	v_exp_f32_e32 v8, v12
	v_exp_f32_e32 v9, v13
	s_waitcnt lgkmcnt(4)
	v_mfma_f32_32x32x16_bf16 v[34:49], v[238:241], v[82:85], v[34:49]
	ds_read_b128 v[234:237], v220 offset:48736
	v_cvt_pk_bf16_f32 v90, v4, v5
	v_add_f32_e32 v17, v17, v6
	v_fmamk_f32 v14, v96, 0x3e0293ee, v191
	v_add_f32_e32 v17, v17, v7
	v_fmamk_f32 v15, v97, 0x3e0293ee, v191
	v_exp_f32_e32 v10, v14
	s_waitcnt lgkmcnt(4)
	v_mfma_f32_32x32x16_bf16 v[18:33], v[242:245], v[82:85], v[18:33]
	v_exp_f32_e32 v11, v15
	v_cvt_pk_bf16_f32 v91, v6, v7
	v_add_f32_e32 v17, v17, v8
	v_add_f32_e32 v17, v17, v9
	v_cvt_pk_bf16_f32 v92, v8, v9
	v_add_f32_e32 v17, v17, v10
	v_add_f32_e32 v17, v17, v11
	v_cvt_pk_bf16_f32 v93, v10, v11
	v_add_f32_e32 v219, v16, v17
	s_waitcnt lgkmcnt(3)
	v_mfma_f32_32x32x16_bf16 v[66:81], v[222:225], v[90:93], v[66:81]
	v_fmac_f32_e32 v219, v216, v2
	s_waitcnt lgkmcnt(2)
	v_mfma_f32_32x32x16_bf16 v[50:65], v[226:229], v[90:93], v[50:65]
	s_waitcnt lgkmcnt(1)
	v_mfma_f32_32x32x16_bf16 v[34:49], v[230:233], v[90:93], v[34:49]
	s_waitcnt lgkmcnt(0)
	v_mfma_f32_32x32x16_bf16 v[18:33], v[234:237], v[90:93], v[18:33]
	s_setprio 0
	s_branch .Lpostpv_slc
